# v132 plus static priority raise for waves 4-7 through the prologue phase (free-running waves: HBM streaming + table generation)
# baseline (speedup 1.0000x reference)
; #define PROBE_BEGIN(id) unsigned long long pb_t0_##id = 0; if (PROBE_SEC == (id)) pb_t0_##id = __builtin_amdgcn_s_memrealtime();
; #define PROBE_END(id) if (PROBE_SEC == (id)) { const unsigned long long pb_t1_ = __builtin_amdgcn_s_memrealtime(), pb_dt_ = pb_t1_ - pb_t0_##id; while (__builtin_amdgcn_s_memrealtime() - pb_t1_ < pb_dt_) __builtin_amdgcn_s_sleep(4); }
; #define SEAM(k) do { if (IN(k) && IN((k) + 1)) { for (int br_ = 0; br_ < BAR_REPEAT; ++br_) xcd_barrier(bar); } } while (0)
; __device__ __forceinline__ void gen_ssm_params(Frame& F, int g, SsmParams& P) {
;     const float *a_re = F.in[6], *a_im = F.in[7], *log_dt = F.in[8], *b_re = F.in[9], *b_im = F.in[10], *c_re = F.in[11], *c_im = F.in[12];
;     const int tid = F.tid;
; #pragma unroll
;     for (int d = 0; d < 2; ++d) { const int p = tid & 63; P.lr1[d] = a_re[(d * NG + g) * 64 + p]; P.li1[d] = a_im[(d * NG + g) * 64 + p]; P.ld1[d] = log_dt[d * NG + g]; }
; #pragma unroll
;     for (int k = 0; k < 4; ++k) { const int e = tid + 512 * k, d = e >> 10, p = (e >> 4) & 63, c = e & 15;
;         P.lr2[k] = a_re[(d * NG + g) * 64 + p]; P.li2[k] = a_im[(d * NG + g) * 64 + p]; P.ld2[k] = log_dt[d * NG + g];
;         P.bx[k] = b_re[((d * NG + g) * 64 + p) * 16 + c]; P.by[k] = b_im[((d * NG + g) * 64 + p) * 16 + c]; }
; #pragma unroll
;     for (int k = 0; k < 4; ++k) { const int e = tid + 512 * k, d = e >> 10, c = (e >> 6) & 15, p = e & 63; P.cr[k] = c_re[((d * NG + g) * 16 + c) * 64 + p]; P.ci[k] = c_im[((d * NG + g) * 16 + c) * 64 + p]; }
; __global__ void __launch_bounds__(NWAVES * 64, 2) hybrid_fwd(Args args) {
;     ...
;     if (IN(0)) { PROBE_BEGIN(20) p0_prologue(F, 7); __syncthreads(); PROBE_END(20) if (REPEAT_MASK & 1) { p0_prologue(F, REPEAT_P0); __syncthreads(); } SEAM(0); }
.LBB0_16:
	s_load_dwordx16 s[12:27], s[0:1], 0x0
	s_load_dwordx16 s[36:51], s[0:1], 0x40
	s_cmp_lt_i32 s34, 1
	s_cselect_b64 s[0:1], -1, 0
	s_cmp_gt_i32 s35, 0
	s_cselect_b64 s[4:5], -1, 0
	s_and_b64 s[0:1], s[0:1], s[4:5]
	s_andn2_b64 vcc, exec, s[0:1]
	v_readfirstlane_b32 s4, v0
	s_nop 3
	s_bitcmp1_b32 s4, 8
	s_cbranch_scc0 .Lp0_lo
	s_setprio 1
.Lp0_lo:
	v_and_b32_e32 v164, 63, v0
	s_cbranch_vccnz .LBB0_159
	s_lshr_b32 s63, s97, 6
	s_lshl_b32 s76, s82, 3
	s_ashr_i32 s74, s82, 3
	s_add_i32 s70, s76, s63
	s_lshl_b32 s72, s81, 3
	s_lshl_b32 s4, s74, 6
	s_ashr_i32 s75, s74, 31
	s_ashr_i32 s73, s72, 31
	s_ashr_i32 s71, s70, 31
	v_or_b32_e32 v2, s4, v164
	s_lshl_b64 s[0:1], s[74:75], 2
	v_ashrrev_i32_e32 v3, 31, v2
	s_waitcnt lgkmcnt(0)
	s_add_u32 s0, s36, s0
	v_lshlrev_b64 v[2:3], 2, v[2:3]
	s_addc_u32 s1, s37, s1
	s_add_i32 s5, s74, 32
	v_lshl_add_u64 v[4:5], s[24:25], 0, v[2:3]
	v_lshl_add_u64 v[2:3], s[26:27], 0, v[2:3]
	s_lshl_b32 s6, s5, 6
	global_load_dword v183, v[2:3], off
	v_or_b32_e32 v2, s6, v164
	v_ashrrev_i32_e32 v3, 31, v2
	v_lshlrev_b64 v[2:3], 2, v[2:3]
	global_load_dword v182, v[4:5], off
	v_lshl_add_u64 v[4:5], s[24:25], 0, v[2:3]
	v_lshl_add_u64 v[2:3], s[26:27], 0, v[2:3]
	v_lshrrev_b32_e32 v9, 4, v0
	v_mov_b32_e32 v149, 0
	global_load_dword v184, v[4:5], off
	global_load_dword v185, v[2:3], off
	global_load_dword v176, v149, s[0:1]
	global_load_dword v167, v149, s[0:1] offset:128
	v_or_b32_e32 v2, s4, v9
	v_and_b32_e32 v8, 15, v0
	v_ashrrev_i32_e32 v3, 31, v2
	v_lshlrev_b64 v[4:5], 2, v[2:3]
	v_lshl_or_b32 v2, v2, 4, v8
	v_ashrrev_i32_e32 v3, 31, v2
	v_lshl_add_u64 v[6:7], s[24:25], 0, v[4:5]
	v_lshl_add_u64 v[4:5], s[26:27], 0, v[4:5]
	v_lshlrev_b64 v[2:3], 2, v[2:3]
	global_load_dword v180, v[4:5], off
	v_lshl_add_u64 v[4:5], s[38:39], 0, v[2:3]
	v_lshl_add_u64 v[2:3], s[40:41], 0, v[2:3]
	v_or_b32_e32 v1, 0x200, v0
	global_load_dword v178, v[2:3], off
	v_lshrrev_b32_e32 v2, 4, v1
	v_or_b32_e32 v2, s4, v2
	v_ashrrev_i32_e32 v3, 31, v2
	global_load_dword v177, v[4:5], off
	v_lshlrev_b64 v[4:5], 2, v[2:3]
	v_lshl_or_b32 v2, v2, 4, v8
	v_ashrrev_i32_e32 v3, 31, v2
	global_load_dword v179, v[6:7], off
	v_lshl_add_u64 v[6:7], s[24:25], 0, v[4:5]
	v_lshl_add_u64 v[4:5], s[26:27], 0, v[4:5]
	v_lshlrev_b64 v[2:3], 2, v[2:3]
	global_load_dword v175, v[4:5], off
	v_lshl_add_u64 v[4:5], s[38:39], 0, v[2:3]
	v_lshl_add_u64 v[2:3], s[40:41], 0, v[2:3]
	global_load_dword v173, v[2:3], off
	v_or_b32_e32 v2, s6, v9
	v_ashrrev_i32_e32 v3, 31, v2
	global_load_dword v172, v[4:5], off
	v_lshlrev_b64 v[4:5], 2, v[2:3]
	v_lshl_or_b32 v2, v2, 4, v8
	v_ashrrev_i32_e32 v3, 31, v2
	global_load_dword v174, v[6:7], off
	v_lshl_add_u64 v[6:7], s[24:25], 0, v[4:5]
	v_lshl_add_u64 v[4:5], s[26:27], 0, v[4:5]
	v_lshlrev_b64 v[2:3], 2, v[2:3]
	global_load_dword v171, v[4:5], off
	v_lshl_add_u64 v[4:5], s[38:39], 0, v[2:3]
	v_lshl_add_u64 v[2:3], s[40:41], 0, v[2:3]
	v_or_b32_e32 v147, 0x600, v0
	global_load_dword v169, v[2:3], off
	v_lshrrev_b32_e32 v2, 4, v147
	v_and_or_b32 v2, v2, 63, s6
	v_ashrrev_i32_e32 v3, 31, v2
	global_load_dword v168, v[4:5], off
	v_lshlrev_b64 v[4:5], 2, v[2:3]
	v_lshl_or_b32 v2, v2, 4, v8
	v_ashrrev_i32_e32 v3, 31, v2
	global_load_dword v170, v[6:7], off
	v_lshl_add_u64 v[6:7], s[24:25], 0, v[4:5]
	v_lshl_add_u64 v[4:5], s[26:27], 0, v[4:5]
	v_lshlrev_b64 v[2:3], 2, v[2:3]
	global_load_dword v154, v[6:7], off
	global_load_dword v157, v[4:5], off
	v_lshl_add_u64 v[4:5], s[38:39], 0, v[2:3]
	v_lshl_add_u64 v[2:3], s[40:41], 0, v[2:3]
	v_and_b32_e32 v6, 0x1c0, v0
	s_lshl_b32 s0, s74, 10
	global_load_dword v151, v[2:3], off
	v_or3_b32 v2, s0, v6, v164
	v_ashrrev_i32_e32 v3, 31, v2
	v_lshlrev_b64 v[2:3], 2, v[2:3]
	global_load_dword v150, v[4:5], off
	v_lshl_add_u64 v[4:5], s[42:43], 0, v[2:3]
	v_lshl_add_u64 v[2:3], s[44:45], 0, v[2:3]
	global_load_dword v153, v[2:3], off
	s_movk_i32 s1, 0x3c0
	v_mov_b32_e32 v2, 0x200
	v_bitop3_b32 v2, v0, s1, v2 bitop3:0xc8
	v_or3_b32 v2, s0, v2, v164
	v_ashrrev_i32_e32 v3, 31, v2
	v_lshlrev_b64 v[2:3], 2, v[2:3]
	global_load_dword v152, v[4:5], off
	v_lshl_add_u64 v[4:5], s[42:43], 0, v[2:3]
	v_lshl_add_u64 v[2:3], s[44:45], 0, v[2:3]
	s_add_i32 s0, s0, 0x8000
	global_load_dword v156, v[2:3], off
	v_or3_b32 v2, s0, v6, v164
	v_ashrrev_i32_e32 v3, 31, v2
	v_lshlrev_b64 v[2:3], 2, v[2:3]
	global_load_dword v155, v[4:5], off
	v_lshl_add_u64 v[4:5], s[42:43], 0, v[2:3]
; #define GAS __attribute__((address_space(1)))
; __device__ __forceinline__ void xn_load(Frame& F, XnBatch& B, const float* x0) {
; #pragma unroll
;     for (int r = 0; r < 4; ++r) { const GAS f32x4* xr = (const GAS f32x4*)(x0 + (size_t)r * DM) + 2 * F.lane;
;         B.v[r][0] = __builtin_nontemporal_load(xr); B.v[r][1] = __builtin_nontemporal_load(xr + 1); B.v[r][2] = __builtin_nontemporal_load(xr + 128); B.v[r][3] = __builtin_nontemporal_load(xr + 129); }
; }
; __device__ __forceinline__ void p0_prologue(Frame& F, int parts) {
;     ...
;     const GAS f32x4* gr = (const GAS f32x4*)F.in[1] + 2 * F.lane; const f32x4 gn[4] = {gr[0], gr[1], gr[128], gr[129]};
;     const size_t xst = (size_t)4 * NGW * DM; const size_t xo = (size_t)4 * gw * DM;
;     ...
;     XnBatch XA, XB;
;     SsmParams SP; gen_ssm_params(F, F.vcu >> 3, SP);
;     xn_load(F, XA, x + xo); xn_load(F, XB, x + xo + xst);
	v_lshl_add_u64 v[2:3], s[44:45], 0, v[2:3]
	global_load_dword v163, v[2:3], off
	v_mov_b32_e32 v2, 0x600
	v_bitop3_b32 v2, v0, s1, v2 bitop3:0xc8
	s_lshl_b32 s0, s5, 10
	v_or3_b32 v2, s0, v2, v164
	v_ashrrev_i32_e32 v3, 31, v2
	s_lshl_b64 s[0:1], s[70:71], 14
	v_lshlrev_b64 v[2:3], 2, v[2:3]
	s_add_u32 s24, s12, s0
	v_lshlrev_b32_e32 v148, 5, v164
	global_load_dword v158, v[4:5], off
	v_lshl_add_u64 v[4:5], s[42:43], 0, v[2:3]
	v_lshl_add_u64 v[2:3], s[44:45], 0, v[2:3]
	s_addc_u32 s25, s13, s1
	global_load_dword v166, v[2:3], off
	v_lshl_add_u64 v[2:3], s[24:25], 0, v[148:149]
	s_movk_i32 s26, 0x2000
	v_add_co_u32_e32 v6, vcc, s26, v2
	s_lshl_b64 s[0:1], s[72:73], 14
	s_mov_b64 s[4:5], 0x1000
	v_addc_co_u32_e32 v7, vcc, 0, v3, vcc
	s_mov_b64 s[8:9], 0x2000
	s_mov_b64 s[6:7], 0x3000
	s_movk_i32 s27, 0x3000
	s_add_u32 s0, s24, s0
	global_load_dword v165, v[4:5], off
	v_lshl_add_u64 v[4:5], v[2:3], 0, s[4:5]
	v_lshl_add_u64 v[8:9], v[2:3], 0, s[8:9]
	v_lshl_add_u64 v[10:11], v[2:3], 0, s[6:7]
	v_add_co_u32_e32 v2, vcc, s27, v2
	s_addc_u32 s1, s25, s1
	s_nop 0
	v_addc_co_u32_e32 v3, vcc, 0, v3, vcc
	v_lshl_add_u64 v[12:13], s[0:1], 0, v[148:149]
	v_add_co_u32_e32 v16, vcc, s26, v12
	v_lshl_add_u64 v[14:15], v[12:13], 0, s[4:5]
	s_nop 0
	v_addc_co_u32_e32 v17, vcc, 0, v13, vcc
	v_add_co_u32_e32 v20, vcc, s27, v12
	v_lshl_add_u64 v[18:19], v[12:13], 0, s[8:9]
	s_nop 0
	v_addc_co_u32_e32 v21, vcc, 0, v13, vcc
	v_lshl_add_u64 v[12:13], v[12:13], 0, s[6:7]
	global_load_dwordx4 v[126:129], v[6:7], off offset:-4096 nt
	global_load_dwordx4 v[106:109], v[6:7], off nt
	global_load_dwordx4 v[122:125], v[4:5], off offset:16 nt
	global_load_dwordx4 v[118:121], v[4:5], off offset:2048 nt
	global_load_dwordx4 v[114:117], v[4:5], off offset:2064 nt
	global_load_dwordx4 v[110:113], v[8:9], off offset:16 nt
	global_load_dwordx4 v[98:101], v[8:9], off offset:2064 nt
	global_load_dwordx4 v[102:105], v[8:9], off offset:2048 nt
	global_load_dwordx4 v[94:97], v[2:3], off nt
	global_load_dwordx4 v[82:85], v[10:11], off offset:2064 nt
	global_load_dwordx4 v[90:93], v[10:11], off offset:16 nt
	global_load_dwordx4 v[86:89], v[10:11], off offset:2048 nt
	global_load_dwordx4 v[62:65], v[16:17], off offset:-4096 nt
	global_load_dwordx4 v[42:45], v[16:17], off nt
	global_load_dwordx4 v[58:61], v[14:15], off offset:16 nt
	global_load_dwordx4 v[54:57], v[14:15], off offset:2048 nt
	global_load_dwordx4 v[50:53], v[14:15], off offset:2064 nt
	global_load_dwordx4 v[46:49], v[18:19], off offset:16 nt
	global_load_dwordx4 v[34:37], v[18:19], off offset:2064 nt
	global_load_dwordx4 v[38:41], v[18:19], off offset:2048 nt
	global_load_dwordx4 v[30:33], v[20:21], off nt
	s_nop 0
	global_load_dwordx4 v[18:21], v[12:13], off offset:2064 nt
	global_load_dwordx4 v[26:29], v[12:13], off offset:16 nt
	global_load_dwordx4 v[22:25], v[12:13], off offset:2048 nt
	s_nop 0
	global_load_dwordx4 v[10:13], v148, s[14:15] offset:16
	global_load_dwordx4 v[14:17], v148, s[14:15]
	global_load_dwordx4 v[2:5], v148, s[14:15] offset:2064
	global_load_dwordx4 v[6:9], v148, s[14:15] offset:2048
	global_load_dwordx4 v[138:141], v148, s[24:25] offset:16 nt
	global_load_dwordx4 v[142:145], v148, s[24:25] nt
	global_load_dwordx4 v[130:133], v148, s[24:25] offset:2064 nt
	global_load_dwordx4 v[134:137], v148, s[24:25] offset:2048 nt
	global_load_dwordx4 v[74:77], v148, s[0:1] offset:16 nt
	global_load_dwordx4 v[78:81], v148, s[0:1] nt
	global_load_dwordx4 v[66:69], v148, s[0:1] offset:2064 nt
	global_load_dwordx4 v[70:73], v148, s[0:1] offset:2048 nt
	v_lshrrev_b32_e32 v159, 6, v0
	v_lshrrev_b32_e32 v161, 5, v1
	v_lshrrev_b32_e32 v160, 5, v147
	s_mov_b64 s[14:15], 0
	s_movk_i32 s33, 0x840
	s_mov_b32 s36, 0x3fb8aa3b
	s_mov_b32 s37, 0xc2ce8ed0
	s_mov_b32 s38, 0x42b17218
	s_brev_b32 s39, 18
	s_mov_b32 s40, 0xfe5163ab
	s_mov_b32 s41, 0x3c439041
	s_mov_b32 s42, 0xdb629599
	s_mov_b32 s43, 0xf534ddc0
	s_mov_b32 s44, 0xfc2757d1
	s_mov_b32 s45, 0x4e441529
	s_mov_b32 s78, 0xa2f9836e
	s_mov_b32 s79, 0x3fc90fda
	s_mov_b32 s80, 0x3f22f983
	s_mov_b32 s83, 0xbfc90fda
	s_brev_b32 s84, 1
	s_movk_i32 s85, 0x1f8
	s_movk_i32 s86, 0xe7f
	v_mov_b32_e32 v186, 0x3c0881c4
	v_mov_b32_e32 v187, 0xbab64f3b
	v_mov_b32_e32 v188, 0x7f800000
	v_not_b32_e32 v189, 63
	v_not_b32_e32 v190, 31
	v_mov_b32_e32 v191, 0x7fc00000
	v_mov_b32_e32 v192, v159
	v_mov_b32_e32 v193, v0
	v_lshlrev_b32_e32 v146, 1, v164
	s_branch .LBB0_19
